# P6-epilogue-gate-loads-up-front
# speedup vs baseline: 1.0334x; 1.0007x over previous
; __device__ __forceinline__ void unpack8(u32x4 w, float* f) { f[0] = lo16(w.x); f[1] = hi16(w.x); f[2] = lo16(w.y); f[3] = hi16(w.y); f[4] = lo16(w.z); f[5] = hi16(w.z); f[6] = lo16(w.w); f[7] = hi16(w.w); }
; __device__ __forceinline__ u32x4 pack8(const float* f) { u32x4 w; w.x = pk2(f[0], f[1]); w.y = pk2(f[2], f[3]); w.z = pk2(f[4], f[5]); w.w = pk2(f[6], f[7]); return w; }
;     __device__ __forceinline__ void operator()(const f32x4 (&acc)[2][2][4][2], const pg8::Unit& u, int wr, int wc, int fr, int fq) const {
;         const int row0 = u.pm * 256 + wr * 64 + fr, col0 = u.pn * 256 + wc * 32 + 8 * fq;
; #pragma unroll
;         for (int ai = 0; ai < 2; ++ai) {
; #pragma unroll
;             for (int m = 0; m < 4; ++m) { const int row = row0 + ai * 128 + m * 16;
; #pragma unroll
;                 for (int bj = 0; bj < 2; ++bj) { const int col = col0 + bj * 128; float a8[8]; unpack8(*(const u32x4*)(gA + (size_t)row * DM + col), a8);
;                     const f32x4 v0 = acc[ai][bj][m][0], v1 = acc[ai][bj][m][1];
;                     float o[8] = {v0[0] * a8[0], v0[1] * a8[1], v0[2] * a8[2], v0[3] * a8[3], v1[0] * a8[4], v1[1] * a8[5], v1[2] * a8[6], v1[3] * a8[7]};
;                     *(u32x4*)(O + (size_t)row * DM + col) = pack8(o); } }
;             asm volatile("" ::: "memory");
;         }
;     }
.LBB0_602:
	v_ashrrev_i32_e32 v169, 31, v168
	v_lshlrev_b64 v[38:39], 11, v[168:169]
	v_ashrrev_i32_e32 v167, 31, v166
	v_lshl_add_u64 v[132:133], s[8:9], 0, v[38:39]
	v_lshlrev_b64 v[36:37], 1, v[166:167]
	v_lshl_add_u64 v[138:139], v[132:133], 0, v[36:37]
	v_lshl_add_u64 v[38:39], s[10:11], 0, v[38:39]
	v_lshl_add_u64 v[38:39], v[38:39], 0, v[36:37]
	v_ashrrev_i32_e32 v171, 31, v170
	v_ashrrev_i32_e32 v173, 31, v172
	v_ashrrev_i32_e32 v175, 31, v174
	v_ashrrev_i32_e32 v177, 31, v176
	v_ashrrev_i32_e32 v179, 31, v178
	v_ashrrev_i32_e32 v153, 31, v152
	v_ashrrev_i32_e32 v137, 31, v136
	s_andn2_b64 vcc, exec, s[6:7]
	s_mov_b64 s[0:1], -1
	v_lshlrev_b64 v[154:155], 11, v[168:169]
	v_lshl_add_u64 v[154:155], s[8:9], 0, v[154:155]
	v_lshl_add_u64 v[154:155], v[154:155], 0, v[36:37]
	global_load_dwordx4 v[198:201], v[154:155], off
	global_load_dwordx4 v[202:205], v[154:155], off offset:256
	v_lshlrev_b64 v[154:155], 11, v[170:171]
	v_lshl_add_u64 v[154:155], s[8:9], 0, v[154:155]
	v_lshl_add_u64 v[154:155], v[154:155], 0, v[36:37]
	global_load_dwordx4 v[206:209], v[154:155], off
	global_load_dwordx4 v[210:213], v[154:155], off offset:256
	v_lshlrev_b64 v[154:155], 11, v[172:173]
	v_lshl_add_u64 v[154:155], s[8:9], 0, v[154:155]
	v_lshl_add_u64 v[154:155], v[154:155], 0, v[36:37]
	global_load_dwordx4 v[214:217], v[154:155], off
	global_load_dwordx4 v[218:221], v[154:155], off offset:256
	v_lshlrev_b64 v[154:155], 11, v[174:175]
	v_lshl_add_u64 v[154:155], s[8:9], 0, v[154:155]
	v_lshl_add_u64 v[154:155], v[154:155], 0, v[36:37]
	global_load_dwordx4 v[222:225], v[154:155], off
	global_load_dwordx4 v[226:229], v[154:155], off offset:256
	v_lshlrev_b64 v[154:155], 11, v[176:177]
	v_lshl_add_u64 v[154:155], s[8:9], 0, v[154:155]
	v_lshl_add_u64 v[154:155], v[154:155], 0, v[36:37]
	global_load_dwordx4 v[230:233], v[154:155], off
	global_load_dwordx4 v[234:237], v[154:155], off offset:256
	v_lshlrev_b64 v[154:155], 11, v[178:179]
	v_lshl_add_u64 v[154:155], s[8:9], 0, v[154:155]
	v_lshl_add_u64 v[154:155], v[154:155], 0, v[36:37]
	global_load_dwordx4 v[238:241], v[154:155], off
	global_load_dwordx4 v[242:245], v[154:155], off offset:256
	v_lshlrev_b64 v[154:155], 11, v[152:153]
	v_lshl_add_u64 v[154:155], s[8:9], 0, v[154:155]
	v_lshl_add_u64 v[154:155], v[154:155], 0, v[36:37]
	global_load_dwordx4 v[246:249], v[154:155], off
	global_load_dwordx4 v[250:253], v[154:155], off offset:256
	v_lshlrev_b64 v[154:155], 11, v[136:137]
	v_lshl_add_u64 v[154:155], s[8:9], 0, v[154:155]
	v_lshl_add_u64 v[154:155], v[154:155], 0, v[36:37]
	global_load_dwordx4 v[144:147], v[154:155], off
	global_load_dwordx4 v[148:151], v[154:155], off offset:256
	s_waitcnt vmcnt(15)
	s_nop 1
	v_mov_b32_e32 v132, v198
	v_mov_b32_e32 v133, v199
	v_mov_b32_e32 v134, v200
	v_mov_b32_e32 v135, v201
	v_lshlrev_b32_e32 v140, 16, v132
	v_and_b32_e32 v141, 0xffff0000, v132
	v_lshlrev_b32_e32 v132, 16, v133
	v_and_b32_e32 v133, 0xffff0000, v133
	v_lshlrev_b32_e32 v142, 16, v134
	v_and_b32_e32 v143, 0xffff0000, v134
	v_lshlrev_b32_e32 v134, 16, v135
	v_and_b32_e32 v135, 0xffff0000, v135
	v_pk_mul_f32 v[4:5], v[4:5], v[140:141]
	v_pk_mul_f32 v[6:7], v[6:7], v[132:133]
	v_pk_mul_f32 v[132:133], v[0:1], v[142:143]
	v_pk_mul_f32 v[134:135], v[2:3], v[134:135]
	v_cvt_pk_bf16_f32 v0, v4, v5
	v_cvt_pk_bf16_f32 v1, v6, v7
	v_cvt_pk_bf16_f32 v2, v132, v133
	v_cvt_pk_bf16_f32 v3, v134, v135
	global_store_dwordx4 v[38:39], v[0:3], off
	v_lshlrev_b64 v[4:5], 11, v[170:171]
	v_lshl_add_u64 v[6:7], s[8:9], 0, v[4:5]
	v_lshl_add_u64 v[6:7], v[6:7], 0, v[36:37]
	v_lshl_add_u64 v[4:5], s[10:11], 0, v[4:5]
	v_lshl_add_u64 v[4:5], v[4:5], 0, v[36:37]
	s_waitcnt vmcnt(15)
	s_nop 1
	v_mov_b32_e32 v0, v202
	v_mov_b32_e32 v1, v203
	v_mov_b32_e32 v2, v204
	v_mov_b32_e32 v3, v205
	v_lshlrev_b32_e32 v132, 16, v0
	v_and_b32_e32 v133, 0xffff0000, v0
	v_lshlrev_b32_e32 v0, 16, v1
	v_and_b32_e32 v1, 0xffff0000, v1
	v_lshlrev_b32_e32 v134, 16, v2
	v_and_b32_e32 v135, 0xffff0000, v2
	v_lshlrev_b32_e32 v2, 16, v3
	v_and_b32_e32 v3, 0xffff0000, v3
	v_pk_mul_f32 v[12:13], v[12:13], v[132:133]
	v_pk_mul_f32 v[14:15], v[14:15], v[0:1]
	v_pk_mul_f32 v[8:9], v[8:9], v[134:135]
	v_pk_mul_f32 v[10:11], v[10:11], v[2:3]
	v_cvt_pk_bf16_f32 v0, v12, v13
	v_cvt_pk_bf16_f32 v1, v14, v15
	v_cvt_pk_bf16_f32 v2, v8, v9
	v_cvt_pk_bf16_f32 v3, v10, v11
	global_store_dwordx4 v[38:39], v[0:3], off offset:256
	s_waitcnt vmcnt(15)
	s_nop 1
	v_mov_b32_e32 v0, v206
	v_mov_b32_e32 v1, v207
	v_mov_b32_e32 v2, v208
	v_mov_b32_e32 v3, v209
	v_lshlrev_b32_e32 v8, 16, v0
	v_and_b32_e32 v9, 0xffff0000, v0
	v_lshlrev_b32_e32 v0, 16, v1
	v_and_b32_e32 v1, 0xffff0000, v1
	v_lshlrev_b32_e32 v10, 16, v2
	v_and_b32_e32 v11, 0xffff0000, v2
	v_lshlrev_b32_e32 v2, 16, v3
	v_and_b32_e32 v3, 0xffff0000, v3
	v_pk_mul_f32 v[8:9], v[28:29], v[8:9]
	v_pk_mul_f32 v[12:13], v[30:31], v[0:1]
	v_pk_mul_f32 v[10:11], v[24:25], v[10:11]
	v_pk_mul_f32 v[14:15], v[26:27], v[2:3]
	v_cvt_pk_bf16_f32 v0, v8, v9
	v_cvt_pk_bf16_f32 v1, v12, v13
	v_cvt_pk_bf16_f32 v2, v10, v11
	v_cvt_pk_bf16_f32 v3, v14, v15
	global_store_dwordx4 v[4:5], v[0:3], off
	v_lshlrev_b64 v[6:7], 11, v[172:173]
	v_lshl_add_u64 v[8:9], s[8:9], 0, v[6:7]
	v_lshl_add_u64 v[8:9], v[8:9], 0, v[36:37]
	s_waitcnt vmcnt(15)
; __device__ __forceinline__ void unpack8(u32x4 w, float* f) { f[0] = lo16(w.x); f[1] = hi16(w.x); f[2] = lo16(w.y); f[3] = hi16(w.y); f[4] = lo16(w.z); f[5] = hi16(w.z); f[6] = lo16(w.w); f[7] = hi16(w.w); }
; __device__ __forceinline__ u32x4 pack8(const float* f) { u32x4 w; w.x = pk2(f[0], f[1]); w.y = pk2(f[2], f[3]); w.z = pk2(f[4], f[5]); w.w = pk2(f[6], f[7]); return w; }
;     __device__ __forceinline__ void operator()(const f32x4 (&acc)[2][2][4][2], const pg8::Unit& u, int wr, int wc, int fr, int fq) const {
;         const int row0 = u.pm * 256 + wr * 64 + fr, col0 = u.pn * 256 + wc * 32 + 8 * fq;
; #pragma unroll
;         for (int ai = 0; ai < 2; ++ai) {
; #pragma unroll
;             for (int m = 0; m < 4; ++m) { const int row = row0 + ai * 128 + m * 16;
; #pragma unroll
;                 for (int bj = 0; bj < 2; ++bj) { const int col = col0 + bj * 128; float a8[8]; unpack8(*(const u32x4*)(gA + (size_t)row * DM + col), a8);
;                     const f32x4 v0 = acc[ai][bj][m][0], v1 = acc[ai][bj][m][1];
;                     float o[8] = {v0[0] * a8[0], v0[1] * a8[1], v0[2] * a8[2], v0[3] * a8[3], v1[0] * a8[4], v1[1] * a8[5], v1[2] * a8[6], v1[3] * a8[7]};
;                     *(u32x4*)(O + (size_t)row * DM + col) = pack8(o); } }
;             asm volatile("" ::: "memory");
;         }
;     }
	s_nop 1
	v_mov_b32_e32 v0, v210
	v_mov_b32_e32 v1, v211
	v_mov_b32_e32 v2, v212
	v_mov_b32_e32 v3, v213
	v_lshlrev_b32_e32 v10, 16, v0
	v_and_b32_e32 v11, 0xffff0000, v0
	v_lshlrev_b32_e32 v0, 16, v1
	v_and_b32_e32 v1, 0xffff0000, v1
	v_lshlrev_b32_e32 v12, 16, v2
	v_and_b32_e32 v13, 0xffff0000, v2
	v_lshlrev_b32_e32 v2, 16, v3
	v_and_b32_e32 v3, 0xffff0000, v3
	v_pk_mul_f32 v[10:11], v[52:53], v[10:11]
	v_pk_mul_f32 v[14:15], v[54:55], v[0:1]
	v_pk_mul_f32 v[12:13], v[48:49], v[12:13]
	v_pk_mul_f32 v[24:25], v[50:51], v[2:3]
	v_cvt_pk_bf16_f32 v0, v10, v11
	v_cvt_pk_bf16_f32 v1, v14, v15
	v_cvt_pk_bf16_f32 v2, v12, v13
	v_cvt_pk_bf16_f32 v3, v24, v25
	global_store_dwordx4 v[4:5], v[0:3], off offset:256
	v_lshl_add_u64 v[4:5], s[10:11], 0, v[6:7]
	v_lshl_add_u64 v[4:5], v[4:5], 0, v[36:37]
	s_waitcnt vmcnt(15)
	s_nop 1
	v_mov_b32_e32 v0, v214
	v_mov_b32_e32 v1, v215
	v_mov_b32_e32 v2, v216
	v_mov_b32_e32 v3, v217
	v_lshlrev_b32_e32 v6, 16, v0
	v_and_b32_e32 v7, 0xffff0000, v0
	v_lshlrev_b32_e32 v0, 16, v1
	v_and_b32_e32 v1, 0xffff0000, v1
	v_lshlrev_b32_e32 v10, 16, v2
	v_and_b32_e32 v11, 0xffff0000, v2
	v_lshlrev_b32_e32 v2, 16, v3
	v_and_b32_e32 v3, 0xffff0000, v3
	v_pk_mul_f32 v[6:7], v[60:61], v[6:7]
	v_pk_mul_f32 v[12:13], v[62:63], v[0:1]
	v_pk_mul_f32 v[10:11], v[56:57], v[10:11]
	v_pk_mul_f32 v[14:15], v[58:59], v[2:3]
	v_cvt_pk_bf16_f32 v0, v6, v7
	v_cvt_pk_bf16_f32 v1, v12, v13
	v_cvt_pk_bf16_f32 v2, v10, v11
	v_cvt_pk_bf16_f32 v3, v14, v15
	global_store_dwordx4 v[4:5], v[0:3], off
	v_lshlrev_b64 v[6:7], 11, v[174:175]
	v_lshl_add_u64 v[8:9], s[8:9], 0, v[6:7]
	v_lshl_add_u64 v[8:9], v[8:9], 0, v[36:37]
	s_waitcnt vmcnt(15)
	s_nop 1
	v_mov_b32_e32 v0, v218
	v_mov_b32_e32 v1, v219
	v_mov_b32_e32 v2, v220
	v_mov_b32_e32 v3, v221
	v_lshlrev_b32_e32 v10, 16, v0
	v_and_b32_e32 v11, 0xffff0000, v0
	v_lshlrev_b32_e32 v0, 16, v1
	v_and_b32_e32 v1, 0xffff0000, v1
	v_lshlrev_b32_e32 v12, 16, v2
	v_and_b32_e32 v13, 0xffff0000, v2
	v_lshlrev_b32_e32 v2, 16, v3
	v_and_b32_e32 v3, 0xffff0000, v3
	v_pk_mul_f32 v[10:11], v[76:77], v[10:11]
	v_pk_mul_f32 v[14:15], v[78:79], v[0:1]
	v_pk_mul_f32 v[12:13], v[72:73], v[12:13]
	v_pk_mul_f32 v[24:25], v[74:75], v[2:3]
	v_cvt_pk_bf16_f32 v0, v10, v11
	v_cvt_pk_bf16_f32 v1, v14, v15
	v_cvt_pk_bf16_f32 v2, v12, v13
	v_cvt_pk_bf16_f32 v3, v24, v25
	global_store_dwordx4 v[4:5], v[0:3], off offset:256
	v_lshl_add_u64 v[4:5], s[10:11], 0, v[6:7]
	v_lshl_add_u64 v[4:5], v[4:5], 0, v[36:37]
	s_waitcnt vmcnt(15)
	s_nop 1
	v_mov_b32_e32 v0, v222
	v_mov_b32_e32 v1, v223
	v_mov_b32_e32 v2, v224
	v_mov_b32_e32 v3, v225
	v_lshlrev_b32_e32 v6, 16, v0
	v_and_b32_e32 v7, 0xffff0000, v0
	v_lshlrev_b32_e32 v0, 16, v1
	v_and_b32_e32 v1, 0xffff0000, v1
	v_lshlrev_b32_e32 v10, 16, v2
	v_and_b32_e32 v11, 0xffff0000, v2
	v_lshlrev_b32_e32 v2, 16, v3
	v_and_b32_e32 v3, 0xffff0000, v3
	v_pk_mul_f32 v[6:7], v[84:85], v[6:7]
	v_pk_mul_f32 v[12:13], v[86:87], v[0:1]
	v_pk_mul_f32 v[10:11], v[80:81], v[10:11]
	v_pk_mul_f32 v[14:15], v[82:83], v[2:3]
	v_cvt_pk_bf16_f32 v0, v6, v7
	v_cvt_pk_bf16_f32 v1, v12, v13
	v_cvt_pk_bf16_f32 v2, v10, v11
	v_cvt_pk_bf16_f32 v3, v14, v15
	global_store_dwordx4 v[4:5], v[0:3], off
	v_lshlrev_b64 v[6:7], 11, v[176:177]
	v_lshl_add_u64 v[8:9], s[8:9], 0, v[6:7]
	v_lshl_add_u64 v[8:9], v[8:9], 0, v[36:37]
	s_waitcnt vmcnt(15)
	s_nop 1
	v_mov_b32_e32 v0, v226
	v_mov_b32_e32 v1, v227
	v_mov_b32_e32 v2, v228
	v_mov_b32_e32 v3, v229
	v_lshlrev_b32_e32 v10, 16, v0
	v_and_b32_e32 v11, 0xffff0000, v0
	v_lshlrev_b32_e32 v0, 16, v1
	v_and_b32_e32 v1, 0xffff0000, v1
	v_lshlrev_b32_e32 v12, 16, v2
	v_and_b32_e32 v13, 0xffff0000, v2
	v_lshlrev_b32_e32 v2, 16, v3
	v_and_b32_e32 v3, 0xffff0000, v3
	v_pk_mul_f32 v[10:11], v[100:101], v[10:11]
	v_pk_mul_f32 v[14:15], v[102:103], v[0:1]
	v_pk_mul_f32 v[12:13], v[96:97], v[12:13]
	v_pk_mul_f32 v[24:25], v[98:99], v[2:3]
	v_cvt_pk_bf16_f32 v0, v10, v11
	v_cvt_pk_bf16_f32 v1, v14, v15
	v_cvt_pk_bf16_f32 v2, v12, v13
	v_cvt_pk_bf16_f32 v3, v24, v25
	global_store_dwordx4 v[4:5], v[0:3], off offset:256
	v_lshl_add_u64 v[4:5], s[10:11], 0, v[6:7]
	v_lshl_add_u64 v[4:5], v[4:5], 0, v[36:37]
	s_waitcnt vmcnt(15)
	s_nop 1
	v_mov_b32_e32 v0, v230
	v_mov_b32_e32 v1, v231
	v_mov_b32_e32 v2, v232
	v_mov_b32_e32 v3, v233
	v_lshlrev_b32_e32 v6, 16, v0
	v_and_b32_e32 v7, 0xffff0000, v0
	v_lshlrev_b32_e32 v0, 16, v1
	v_and_b32_e32 v1, 0xffff0000, v1
	v_lshlrev_b32_e32 v10, 16, v2
	v_and_b32_e32 v11, 0xffff0000, v2
	v_lshlrev_b32_e32 v2, 16, v3
	v_and_b32_e32 v3, 0xffff0000, v3
	v_pk_mul_f32 v[6:7], v[116:117], v[6:7]
	v_pk_mul_f32 v[12:13], v[118:119], v[0:1]
	v_pk_mul_f32 v[10:11], v[112:113], v[10:11]
	v_pk_mul_f32 v[14:15], v[114:115], v[2:3]
	v_cvt_pk_bf16_f32 v0, v6, v7
	v_cvt_pk_bf16_f32 v1, v12, v13
	v_cvt_pk_bf16_f32 v2, v10, v11
	v_cvt_pk_bf16_f32 v3, v14, v15
	global_store_dwordx4 v[4:5], v[0:3], off
	v_lshlrev_b64 v[6:7], 11, v[178:179]
	v_lshl_add_u64 v[8:9], s[8:9], 0, v[6:7]
	v_lshl_add_u64 v[8:9], v[8:9], 0, v[36:37]
	s_waitcnt vmcnt(15)
; __device__ __forceinline__ void unpack8(u32x4 w, float* f) { f[0] = lo16(w.x); f[1] = hi16(w.x); f[2] = lo16(w.y); f[3] = hi16(w.y); f[4] = lo16(w.z); f[5] = hi16(w.z); f[6] = lo16(w.w); f[7] = hi16(w.w); }
; __device__ __forceinline__ u32x4 pack8(const float* f) { u32x4 w; w.x = pk2(f[0], f[1]); w.y = pk2(f[2], f[3]); w.z = pk2(f[4], f[5]); w.w = pk2(f[6], f[7]); return w; }
; #define PG8_BAR __builtin_amdgcn_s_barrier()
;     ...
;         if constexpr (ALIGN_EPI) { if (wr == 0) PG8_BAR; }
;         if constexpr (!Epi::AFTER_DRAIN) { E(acc, cur, wr, wc, fr, fq); }
;         if (!has_next) break;
; #pragma unroll
;         for (int a = 0; a < 2; ++a)
; #pragma unroll
;             for (int b = 0; b < 2; ++b)
; #pragma unroll
;                 for (int m = 0; m < 4; ++m)
; #pragma unroll
;                     for (int n = 0; n < 2; ++n) acc[a][b][m][n] = (f32x4){0.f, 0.f, 0.f, 0.f};
;         cur = nxt; cA = nA; cB = nB; ++ui;
;         if constexpr (ALIGN_EPI) { if (wr == 1) PG8_BAR; }
;     __device__ __forceinline__ void operator()(const f32x4 (&acc)[2][2][4][2], const pg8::Unit& u, int wr, int wc, int fr, int fq) const {
;         const int row0 = u.pm * 256 + wr * 64 + fr, col0 = u.pn * 256 + wc * 32 + 8 * fq;
; #pragma unroll
;         for (int ai = 0; ai < 2; ++ai) {
; #pragma unroll
;             for (int m = 0; m < 4; ++m) { const int row = row0 + ai * 128 + m * 16;
; #pragma unroll
;                 for (int bj = 0; bj < 2; ++bj) { const int col = col0 + bj * 128; float a8[8]; unpack8(*(const u32x4*)(gA + (size_t)row * DM + col), a8);
;                     const f32x4 v0 = acc[ai][bj][m][0], v1 = acc[ai][bj][m][1];
;                     float o[8] = {v0[0] * a8[0], v0[1] * a8[1], v0[2] * a8[2], v0[3] * a8[3], v1[0] * a8[4], v1[1] * a8[5], v1[2] * a8[6], v1[3] * a8[7]};
;                     *(u32x4*)(O + (size_t)row * DM + col) = pack8(o); } }
;             asm volatile("" ::: "memory");
;         }
;     }
	s_nop 1
	v_mov_b32_e32 v0, v234
	v_mov_b32_e32 v1, v235
	v_mov_b32_e32 v2, v236
	v_mov_b32_e32 v3, v237
	v_lshlrev_b32_e32 v10, 16, v0
	v_and_b32_e32 v11, 0xffff0000, v0
	v_lshlrev_b32_e32 v0, 16, v1
	v_and_b32_e32 v1, 0xffff0000, v1
	v_lshlrev_b32_e32 v12, 16, v2
	v_and_b32_e32 v13, 0xffff0000, v2
	v_lshlrev_b32_e32 v2, 16, v3
	v_and_b32_e32 v3, 0xffff0000, v3
	v_pk_mul_f32 v[10:11], v[124:125], v[10:11]
	v_pk_mul_f32 v[14:15], v[126:127], v[0:1]
	v_pk_mul_f32 v[12:13], v[120:121], v[12:13]
	v_pk_mul_f32 v[24:25], v[122:123], v[2:3]
	v_cvt_pk_bf16_f32 v0, v10, v11
	v_cvt_pk_bf16_f32 v1, v14, v15
	v_cvt_pk_bf16_f32 v2, v12, v13
	v_cvt_pk_bf16_f32 v3, v24, v25
	global_store_dwordx4 v[4:5], v[0:3], off offset:256
	v_lshl_add_u64 v[4:5], s[10:11], 0, v[6:7]
	v_lshl_add_u64 v[4:5], v[4:5], 0, v[36:37]
	s_waitcnt vmcnt(15)
	s_nop 1
	v_mov_b32_e32 v0, v238
	v_mov_b32_e32 v1, v239
	v_mov_b32_e32 v2, v240
	v_mov_b32_e32 v3, v241
	v_lshlrev_b32_e32 v6, 16, v0
	v_and_b32_e32 v7, 0xffff0000, v0
	v_lshlrev_b32_e32 v0, 16, v1
	v_and_b32_e32 v1, 0xffff0000, v1
	v_lshlrev_b32_e32 v10, 16, v2
	v_and_b32_e32 v11, 0xffff0000, v2
	v_lshlrev_b32_e32 v2, 16, v3
	v_and_b32_e32 v3, 0xffff0000, v3
	v_pk_mul_f32 v[6:7], v[128:129], v[6:7]
	v_pk_mul_f32 v[12:13], v[130:131], v[0:1]
	v_pk_mul_f32 v[10:11], v[104:105], v[10:11]
	v_pk_mul_f32 v[14:15], v[106:107], v[2:3]
	v_cvt_pk_bf16_f32 v0, v6, v7
	v_cvt_pk_bf16_f32 v1, v12, v13
	v_cvt_pk_bf16_f32 v2, v10, v11
	v_cvt_pk_bf16_f32 v3, v14, v15
	global_store_dwordx4 v[4:5], v[0:3], off
	v_lshlrev_b64 v[6:7], 11, v[152:153]
	v_lshl_add_u64 v[8:9], s[8:9], 0, v[6:7]
	v_lshl_add_u64 v[8:9], v[8:9], 0, v[36:37]
	s_waitcnt vmcnt(15)
	s_nop 1
	v_mov_b32_e32 v0, v242
	v_mov_b32_e32 v1, v243
	v_mov_b32_e32 v2, v244
	v_mov_b32_e32 v3, v245
	v_lshlrev_b32_e32 v10, 16, v0
	v_and_b32_e32 v11, 0xffff0000, v0
	v_lshlrev_b32_e32 v0, 16, v1
	v_and_b32_e32 v1, 0xffff0000, v1
	v_lshlrev_b32_e32 v12, 16, v2
	v_and_b32_e32 v13, 0xffff0000, v2
	v_lshlrev_b32_e32 v2, 16, v3
	v_and_b32_e32 v3, 0xffff0000, v3
	v_pk_mul_f32 v[10:11], v[108:109], v[10:11]
	v_pk_mul_f32 v[14:15], v[110:111], v[0:1]
	v_pk_mul_f32 v[12:13], v[88:89], v[12:13]
	v_pk_mul_f32 v[24:25], v[90:91], v[2:3]
	v_cvt_pk_bf16_f32 v0, v10, v11
	v_cvt_pk_bf16_f32 v1, v14, v15
	v_cvt_pk_bf16_f32 v2, v12, v13
	v_cvt_pk_bf16_f32 v3, v24, v25
	global_store_dwordx4 v[4:5], v[0:3], off offset:256
	v_lshl_add_u64 v[4:5], s[10:11], 0, v[6:7]
	v_lshl_add_u64 v[4:5], v[4:5], 0, v[36:37]
	s_waitcnt vmcnt(15)
	s_nop 1
	v_mov_b32_e32 v0, v246
	v_mov_b32_e32 v1, v247
	v_mov_b32_e32 v2, v248
	v_mov_b32_e32 v3, v249
	v_lshlrev_b32_e32 v6, 16, v0
	v_and_b32_e32 v7, 0xffff0000, v0
	v_lshlrev_b32_e32 v0, 16, v1
	v_and_b32_e32 v1, 0xffff0000, v1
	v_lshlrev_b32_e32 v10, 16, v2
	v_and_b32_e32 v11, 0xffff0000, v2
	v_lshlrev_b32_e32 v2, 16, v3
	v_and_b32_e32 v3, 0xffff0000, v3
	v_pk_mul_f32 v[6:7], v[68:69], v[6:7]
	v_pk_mul_f32 v[12:13], v[70:71], v[0:1]
	v_pk_mul_f32 v[10:11], v[64:65], v[10:11]
	v_pk_mul_f32 v[14:15], v[66:67], v[2:3]
	v_cvt_pk_bf16_f32 v0, v6, v7
	v_cvt_pk_bf16_f32 v1, v12, v13
	v_cvt_pk_bf16_f32 v2, v10, v11
	v_cvt_pk_bf16_f32 v3, v14, v15
	global_store_dwordx4 v[4:5], v[0:3], off
	v_lshlrev_b64 v[6:7], 11, v[136:137]
	v_lshl_add_u64 v[8:9], s[8:9], 0, v[6:7]
	v_lshl_add_u64 v[8:9], v[8:9], 0, v[36:37]
	s_waitcnt vmcnt(15)
	s_nop 1
	v_mov_b32_e32 v0, v250
	v_mov_b32_e32 v1, v251
	v_mov_b32_e32 v2, v252
	v_mov_b32_e32 v3, v253
	v_lshlrev_b32_e32 v10, 16, v0
	v_and_b32_e32 v11, 0xffff0000, v0
	v_lshlrev_b32_e32 v0, 16, v1
	v_and_b32_e32 v1, 0xffff0000, v1
	v_lshlrev_b32_e32 v12, 16, v2
	v_and_b32_e32 v13, 0xffff0000, v2
	v_lshlrev_b32_e32 v2, 16, v3
	v_and_b32_e32 v3, 0xffff0000, v3
	v_pk_mul_f32 v[10:11], v[92:93], v[10:11]
	v_pk_mul_f32 v[14:15], v[94:95], v[0:1]
	v_pk_mul_f32 v[12:13], v[44:45], v[12:13]
	v_pk_mul_f32 v[24:25], v[46:47], v[2:3]
	v_cvt_pk_bf16_f32 v0, v10, v11
	v_cvt_pk_bf16_f32 v1, v14, v15
	v_cvt_pk_bf16_f32 v2, v12, v13
	v_cvt_pk_bf16_f32 v3, v24, v25
	global_store_dwordx4 v[4:5], v[0:3], off offset:256
	v_lshl_add_u64 v[4:5], s[10:11], 0, v[6:7]
	v_lshl_add_u64 v[4:5], v[4:5], 0, v[36:37]
	s_waitcnt vmcnt(15)
	s_nop 1
	v_mov_b32_e32 v0, v144
	v_mov_b32_e32 v1, v145
	v_mov_b32_e32 v2, v146
	v_mov_b32_e32 v3, v147
	v_lshlrev_b32_e32 v6, 16, v0
	v_and_b32_e32 v7, 0xffff0000, v0
	v_lshlrev_b32_e32 v0, 16, v1
	v_and_b32_e32 v1, 0xffff0000, v1
	v_lshlrev_b32_e32 v10, 16, v2
	v_and_b32_e32 v11, 0xffff0000, v2
	v_lshlrev_b32_e32 v2, 16, v3
	v_and_b32_e32 v3, 0xffff0000, v3
	v_pk_mul_f32 v[6:7], v[40:41], v[6:7]
	v_pk_mul_f32 v[12:13], v[42:43], v[0:1]
	v_pk_mul_f32 v[10:11], v[32:33], v[10:11]
	v_pk_mul_f32 v[14:15], v[34:35], v[2:3]
	v_cvt_pk_bf16_f32 v0, v6, v7
	v_cvt_pk_bf16_f32 v1, v12, v13
	v_cvt_pk_bf16_f32 v2, v10, v11
	v_cvt_pk_bf16_f32 v3, v14, v15
	global_store_dwordx4 v[4:5], v[0:3], off
	s_waitcnt vmcnt(15)
	s_nop 1
	v_mov_b32_e32 v0, v148
	v_mov_b32_e32 v1, v149
	v_mov_b32_e32 v2, v150
	v_mov_b32_e32 v3, v151
	v_lshlrev_b32_e32 v6, 16, v0
	v_and_b32_e32 v7, 0xffff0000, v0
	v_lshlrev_b32_e32 v0, 16, v1
	v_and_b32_e32 v1, 0xffff0000, v1
	v_lshlrev_b32_e32 v8, 16, v2
	v_and_b32_e32 v9, 0xffff0000, v2
	v_lshlrev_b32_e32 v2, 16, v3
	v_and_b32_e32 v3, 0xffff0000, v3
	v_pk_mul_f32 v[6:7], v[20:21], v[6:7]
	v_pk_mul_f32 v[10:11], v[22:23], v[0:1]
	v_pk_mul_f32 v[8:9], v[16:17], v[8:9]
	v_pk_mul_f32 v[12:13], v[18:19], v[2:3]
	v_cvt_pk_bf16_f32 v0, v6, v7
	v_cvt_pk_bf16_f32 v1, v10, v11
	v_cvt_pk_bf16_f32 v2, v8, v9
	v_cvt_pk_bf16_f32 v3, v12, v13
	global_store_dwordx4 v[4:5], v[0:3], off offset:256
	s_cbranch_vccnz .LBB0_591
	s_andn2_b64 vcc, exec, s[16:17]
	s_cbranch_vccnz .LBB0_590
	s_barrier
	s_branch .LBB0_590
